# dense attention: K-fragment ds_reads hoisted above the LDS-DMA issue block (both head-dim variants)
# speedup vs baseline: 1.0108x; 1.0095x over previous
; #define RAW_BARRIER() do { asm volatile("s_waitcnt lgkmcnt(0)" ::: "memory"); __builtin_amdgcn_s_barrier(); } while (0)
; template <int DK, int QB, bool NA>
; DEVI void attn_item(const AttnArgs& a, unsigned char* smem) {
;     ...
;     if (j + 1 < nt) {
;       if constexpr (DK == 96) asm volatile("s_waitcnt vmcnt(5)" ::: "memory");
;       else                    asm volatile("s_waitcnt vmcnt(4)" ::: "memory");
;     } else {
;       asm volatile("s_waitcnt vmcnt(0)" ::: "memory");
;     }
;     RAW_BARRIER();
;     if (j + 2 < nt) ATT_ISSUE(j + 2, is);
;     is = (is + 1 == S) ? 0 : is + 1;
;     const unsigned cur = lbase + cs * ATT_STAGE;
;     cs = (cs + 1 == S) ? 0 : cs + 1;
;     if (wact) {
;       f32x4 s[4][QB];
; #pragma unroll
;       for (int kb = 0; kb < 4; ++kb)
; #pragma unroll
;         for (int qb = 0; qb < QB; ++qb) s[kb][qb] = (f32x4){0.f, 0.f, 0.f, 0.f};
;       {
;         bf16x8 k0[4], k1[4], k2[4];
;         const unsigned a0 = cur + ka0, a1 = cur + ka1, a2 = cur + kr;
;         k0[0] = ldsr<0>(a0); k0[1] = ldsr<2048>(a0); k0[2] = ldsr<4096>(a0); k0[3] = ldsr<6144>(a0);
;         k1[0] = ldsr<0>(a1); k1[1] = ldsr<2048>(a1); k1[2] = ldsr<4096>(a1); k1[3] = ldsr<6144>(a1);
;         if constexpr (KS == 3) { k2[0] = ldsr<0>(a2); k2[1] = ldsr<1024>(a2); k2[2] = ldsr<2048>(a2); k2[3] = ldsr<3072>(a2); }
;         if constexpr (KS == 3) asm volatile("s_waitcnt lgkmcnt(8)" : "+v"(k0[0]), "+v"(k0[1]), "+v"(k0[2]), "+v"(k0[3]) :: "memory");
;         else                   asm volatile("s_waitcnt lgkmcnt(4)" : "+v"(k0[0]), "+v"(k0[1]), "+v"(k0[2]), "+v"(k0[3]) :: "memory");
;         __builtin_amdgcn_sched_barrier(0);
; #pragma unroll
;         for (int kb = 0; kb < 4; ++kb)
; #pragma unroll
;           for (int qb = 0; qb < QB; ++qb) s[kb][qb] = __builtin_amdgcn_mfma_f32_16x16x32_bf16(k0[kb], qf[qb][0], s[kb][qb], 0, 0, 0);
;         if constexpr (KS == 3) asm volatile("s_waitcnt lgkmcnt(4)" : "+v"(k1[0]), "+v"(k1[1]), "+v"(k1[2]), "+v"(k1[3]) :: "memory");
;         else                   asm volatile("s_waitcnt lgkmcnt(0)" : "+v"(k1[0]), "+v"(k1[1]), "+v"(k1[2]), "+v"(k1[3]) :: "memory");
;         __builtin_amdgcn_sched_barrier(0);
; #pragma unroll
;         for (int kb = 0; kb < 4; ++kb)
; #pragma unroll
;           for (int qb = 0; qb < QB; ++qb) s[kb][qb] = __builtin_amdgcn_mfma_f32_16x16x32_bf16(k1[kb], qf[qb][1], s[kb][qb], 0, 0, 0);
.LBB0_2269:
	s_add_i32 s9, s9, 1
	s_cmp_lt_u32 s9, s61
	s_cselect_b32 s20, s44, s60
	s_mul_i32 s40, s8, 0x5000
	v_add_u32_e32 v0, s40, v185
	v_mad_u64_u32 v[2:3], s[40:41], s20, v205, v[106:107]
	s_mov_b64 s[28:29], 0x700
	v_readfirstlane_b32 s40, v0
	s_mul_i32 s100, s3, 0x5000
	v_or_b32_e32 v208, s100, v183
	v_or_b32_e32 v209, s100, v184
	s_waitcnt vmcnt(4)
	v_lshl_add_u64 v[210:211], v[2:3], 0, s[28:29]
	s_mov_b32 m0, s40
	s_waitcnt lgkmcnt(0)
	s_barrier
	ds_read_b128 v[52:55], v208 offset:0
	ds_read_b128 v[56:59], v208 offset:0x800
	ds_read_b128 v[60:63], v208 offset:0x1000
	ds_read_b128 v[64:67], v208 offset:0x1800
	ds_read_b128 v[68:71], v209 offset:0
	ds_read_b128 v[72:75], v209 offset:0x800
	ds_read_b128 v[76:79], v209 offset:0x1000
	ds_read_b128 v[80:83], v209 offset:0x1800
	global_load_lds_dwordx4 v[210:211], off
	v_add_u32_e32 v210, 0x1000, v0
	s_mov_b64 s[28:29], 0x10f00
	v_readfirstlane_b32 s40, v210
	v_add_u32_e32 v210, 0x3000, v0
	v_lshl_add_u64 v[2:3], v[2:3], 0, s[28:29]
	s_mov_b32 m0, s40
	s_lshl_b64 s[40:41], s[20:21], 1
	v_readfirstlane_b32 s20, v210
	v_add_u32_e32 v0, 0x4000, v0
	global_load_lds_dwordx4 v[2:3], off
	v_lshl_add_u64 v[2:3], v[104:105], 0, s[40:41]
	s_mov_b32 m0, s20
	v_readfirstlane_b32 s20, v0
	global_load_lds_dwordx4 v[2:3], off
	v_lshl_add_u64 v[2:3], v[108:109], 0, s[40:41]
	s_mov_b32 m0, s20
	s_nop 0
	global_load_lds_dwordx4 v[2:3], off
	s_and_saveexec_b64 s[42:43], s[0:1]
	s_cbranch_execz .LBB0_2268
	s_waitcnt lgkmcnt(4)
	s_nop 0
	s_setprio 1
	v_mfma_f32_16x16x32_bf16 v[84:87], v[52:55], v[16:19], 0
	s_waitcnt lgkmcnt(0)
	v_mfma_f32_16x16x32_bf16 v[52:55], v[52:55], v[12:15], 0
	v_mfma_f32_16x16x32_bf16 v[88:91], v[56:59], v[16:19], 0
	v_mfma_f32_16x16x32_bf16 v[56:59], v[56:59], v[12:15], 0
	v_mfma_f32_16x16x32_bf16 v[110:113], v[60:63], v[16:19], 0
	v_mfma_f32_16x16x32_bf16 v[60:63], v[60:63], v[12:15], 0
	v_mfma_f32_16x16x32_bf16 v[114:117], v[64:67], v[16:19], 0
	v_mfma_f32_16x16x32_bf16 v[64:67], v[64:67], v[12:15], 0
	v_mfma_f32_16x16x32_bf16 v[118:121], v[68:71], v[8:11], v[84:87]
	v_add_u32_e32 v0, s100, v129
	v_add_u32_e32 v2, s100, v180
	v_add_u32_e32 v3, s100, v181
	v_mfma_f32_16x16x32_bf16 v[208:211], v[72:75], v[8:11], v[88:91]
	v_mfma_f32_16x16x32_bf16 v[110:113], v[76:79], v[8:11], v[110:113]
	s_nop 2
	v_fma_f32 v120, v120, s92, -v102
	v_fma_f32 v121, v121, s92, -v102
	v_pk_fma_f32 v[122:123], v[118:119], s[92:93], v[102:103] op_sel_hi:[1,0,0] neg_lo:[0,0,1] neg_hi:[0,0,1]
	s_nop 0
	v_pk_fma_f32 v[118:119], v[210:211], s[92:93], v[102:103] op_sel_hi:[1,0,0] neg_lo:[0,0,1] neg_hi:[0,0,1]
	v_mfma_f32_16x16x32_bf16 v[212:215], v[80:83], v[8:11], v[114:117]
	v_max_f32_e32 v125, v118, v119
	v_pk_fma_f32 v[112:113], v[112:113], s[92:93], v[102:103] op_sel_hi:[1,0,0] neg_lo:[0,0,1] neg_hi:[0,0,1]
	v_mfma_f32_16x16x32_bf16 v[96:99], v[68:71], v[4:7], v[52:55]
	v_fma_f32 v116, v208, s92, -v102
	v_fma_f32 v117, v209, s92, -v102
	v_pk_fma_f32 v[114:115], v[110:111], s[92:93], v[102:103] op_sel_hi:[1,0,0] neg_lo:[0,0,1] neg_hi:[0,0,1]
	v_max_f32_e32 v124, v116, v117
	v_mfma_f32_16x16x32_bf16 v[92:95], v[72:75], v[4:7], v[56:59]
	v_add_u32_e32 v54, s100, v182
	v_pk_fma_f32 v[110:111], v[212:213], s[92:93], v[102:103] op_sel_hi:[1,0,0] neg_lo:[0,0,1] neg_hi:[0,0,1]
	s_mov_b32 s20, 0x40c00000
	v_mfma_f32_16x16x32_bf16 v[88:91], v[76:79], v[4:7], v[60:63]
	v_mfma_f32_16x16x32_bf16 v[84:87], v[80:83], v[4:7], v[64:67]
	s_setprio 0
	ds_read_b64 v[80:81], v0 offset:0
	ds_read_b64 v[82:83], v2 offset:0
	ds_read_b64 v[76:77], v0 offset:0x800
	ds_read_b64 v[78:79], v2 offset:0x800
	ds_read_b64 v[72:73], v0 offset:0x1000
	ds_read_b64 v[74:75], v2 offset:0x1000
	ds_read_b64 v[68:69], v0 offset:0x1800
	v_max_f32_e32 v0, v120, v121
	v_max3_f32 v0, v122, v123, v0
	ds_read_b64 v[70:71], v2 offset:0x1800
	ds_read_b64 v[64:65], v3 offset:0
	ds_read_b64 v[66:67], v54 offset:0
	ds_read_b64 v[60:61], v3 offset:0x800
	ds_read_b64 v[62:63], v54 offset:0x800
	ds_read_b64 v[56:57], v3 offset:0x1000
	ds_read_b64 v[58:59], v54 offset:0x1000
	ds_read_b64 v[52:53], v3 offset:0x1800
	v_pk_fma_f32 v[2:3], v[214:215], s[92:93], v[102:103] op_sel_hi:[1,0,0] neg_lo:[0,0,1] neg_hi:[0,0,1]
	v_max3_f32 v0, v0, v124, v125
	v_max_f32_e32 v124, v114, v115
	v_max_f32_e32 v125, v112, v113
	v_max3_f32 v0, v0, v124, v125
	v_max_f32_e32 v124, v110, v111
	v_max_f32_e32 v125, v2, v3
	v_max3_f32 v0, v0, v124, v125
	v_cmp_lt_f32_e32 vcc, s20, v0
	ds_read_b64 v[54:55], v54 offset:0x1800
	s_cbranch_vccz .LBB0_2272
	v_mov_b32_e32 v124, v0
	s_nop 1
	v_permlane16_swap_b32_e32 v0, v124
	v_max_f32_e32 v124, v124, v124
	v_max_f32_e32 v0, v0, v0
	v_max_f32_e32 v0, v0, v124
	v_mov_b32_e32 v124, v0
	s_nop 1
	v_permlane32_swap_b32_e32 v0, v124
	v_max3_f32 v0, v0, v124, 0
	v_exp_f32_e64 v124, -v0
	v_pk_add_f32 v[122:123], v[122:123], v[0:1] op_sel_hi:[1,0] neg_lo:[0,1] neg_hi:[0,1]
	v_pk_add_f32 v[120:121], v[120:121], v[0:1] op_sel_hi:[1,0] neg_lo:[0,1] neg_hi:[0,1]
	v_pk_add_f32 v[116:117], v[116:117], v[0:1] op_sel_hi:[1,0] neg_lo:[0,1] neg_hi:[0,1]
	v_pk_add_f32 v[118:119], v[118:119], v[0:1] op_sel_hi:[1,0] neg_lo:[0,1] neg_hi:[0,1]
	v_pk_add_f32 v[114:115], v[114:115], v[0:1] op_sel_hi:[1,0] neg_lo:[0,1] neg_hi:[0,1]
	v_pk_add_f32 v[112:113], v[112:113], v[0:1] op_sel_hi:[1,0] neg_lo:[0,1] neg_hi:[0,1]
	v_pk_add_f32 v[110:111], v[110:111], v[0:1] op_sel_hi:[1,0] neg_lo:[0,1] neg_hi:[0,1]
	v_pk_add_f32 v[2:3], v[2:3], v[0:1] op_sel_hi:[1,0] neg_lo:[0,1] neg_hi:[0,1]
	v_add_f32_e32 v102, v102, v0
	v_mul_f32_e32 v101, v101, v124
	v_pk_mul_f32 v[50:51], v[50:51], v[124:125] op_sel_hi:[1,0]
	v_pk_mul_f32 v[48:49], v[48:49], v[124:125] op_sel_hi:[1,0]
	v_pk_mul_f32 v[42:43], v[42:43], v[124:125] op_sel_hi:[1,0]
	v_pk_mul_f32 v[40:41], v[40:41], v[124:125] op_sel_hi:[1,0]
	v_pk_mul_f32 v[34:35], v[34:35], v[124:125] op_sel_hi:[1,0]
	v_pk_mul_f32 v[32:33], v[32:33], v[124:125] op_sel_hi:[1,0]
	v_pk_mul_f32 v[26:27], v[26:27], v[124:125] op_sel_hi:[1,0]
	v_pk_mul_f32 v[24:25], v[24:25], v[124:125] op_sel_hi:[1,0]

; template <int DK, int QB, bool NA>
; DEVI void attn_item(const AttnArgs& a, unsigned char* smem) {
;     ...
;     if (j + 1 < nt) {
;       if constexpr (DK == 96) asm volatile("s_waitcnt vmcnt(5)" ::: "memory");
;       else                    asm volatile("s_waitcnt vmcnt(4)" ::: "memory");
;     } else {
;       asm volatile("s_waitcnt vmcnt(0)" ::: "memory");
;     }
;     RAW_BARRIER();
;     if (j + 2 < nt) ATT_ISSUE(j + 2, is);
;     is = (is + 1 == S) ? 0 : is + 1;
;     const unsigned cur = lbase + cs * ATT_STAGE;
;     cs = (cs + 1 == S) ? 0 : cs + 1;
;     if (wact) {
;       f32x4 s[4][QB];
; #pragma unroll
;       for (int kb = 0; kb < 4; ++kb)
; #pragma unroll
;         for (int qb = 0; qb < QB; ++qb) s[kb][qb] = (f32x4){0.f, 0.f, 0.f, 0.f};
;       {
;         bf16x8 k0[4], k1[4], k2[4];
;         const unsigned a0 = cur + ka0, a1 = cur + ka1, a2 = cur + kr;
;         k0[0] = ldsr<0>(a0); k0[1] = ldsr<2048>(a0); k0[2] = ldsr<4096>(a0); k0[3] = ldsr<6144>(a0);
;         k1[0] = ldsr<0>(a1); k1[1] = ldsr<2048>(a1); k1[2] = ldsr<4096>(a1); k1[3] = ldsr<6144>(a1);
;         if constexpr (KS == 3) { k2[0] = ldsr<0>(a2); k2[1] = ldsr<1024>(a2); k2[2] = ldsr<2048>(a2); k2[3] = ldsr<3072>(a2); }
;         if constexpr (KS == 3) asm volatile("s_waitcnt lgkmcnt(8)" : "+v"(k0[0]), "+v"(k0[1]), "+v"(k0[2]), "+v"(k0[3]) :: "memory");
;         else                   asm volatile("s_waitcnt lgkmcnt(4)" : "+v"(k0[0]), "+v"(k0[1]), "+v"(k0[2]), "+v"(k0[3]) :: "memory");
;         __builtin_amdgcn_sched_barrier(0);
; #pragma unroll
;         for (int kb = 0; kb < 4; ++kb)
; #pragma unroll
;           for (int qb = 0; qb < QB; ++qb) s[kb][qb] = __builtin_amdgcn_mfma_f32_16x16x32_bf16(k0[kb], qf[qb][0], s[kb][qb], 0, 0, 0);
;         if constexpr (KS == 3) asm volatile("s_waitcnt lgkmcnt(4)" : "+v"(k1[0]), "+v"(k1[1]), "+v"(k1[2]), "+v"(k1[3]) :: "memory");
;         else                   asm volatile("s_waitcnt lgkmcnt(0)" : "+v"(k1[0]), "+v"(k1[1]), "+v"(k1[2]), "+v"(k1[3]) :: "memory");
;         __builtin_amdgcn_sched_barrier(0);
; #pragma unroll
;         for (int kb = 0; kb < 4; ++kb)
; #pragma unroll
;           for (int qb = 0; qb < QB; ++qb) s[kb][qb] = __builtin_amdgcn_mfma_f32_16x16x32_bf16(k1[kb], qf[qb][1], s[kb][qb], 0, 0, 0);
;         if constexpr (KS == 3) {
.LBB0_2314:
	s_add_i32 s42, s42, 1
	s_cmp_lt_u32 s42, s61
	s_cselect_b32 s20, s43, s60
	s_mul_i32 s2, s9, 0x5000
	v_add_u32_e32 v0, s2, v216
	v_mad_u64_u32 v[2:3], s[2:3], s20, v207, v[114:115]
	v_readfirstlane_b32 s2, v0
	v_add_u32_e32 v221, 0x1000, v0
	s_mul_i32 s100, s8, 0x5000
	v_or_b32_e32 v218, s100, v213
	v_or_b32_e32 v219, s100, v214
	v_add_u32_e32 v220, s100, v215
	s_waitcnt vmcnt(5)
	s_mov_b32 m0, s2
	v_readfirstlane_b32 s2, v221
	s_waitcnt lgkmcnt(0)
	s_barrier
	ds_read_b128 v[60:63], v218 offset:0
	ds_read_b128 v[64:67], v218 offset:0x800
	ds_read_b128 v[68:71], v218 offset:0x1000
	ds_read_b128 v[72:75], v218 offset:0x1800
	ds_read_b128 v[76:79], v219 offset:0
	ds_read_b128 v[80:83], v219 offset:0x800
	ds_read_b128 v[84:87], v219 offset:0x1000
	ds_read_b128 v[88:91], v219 offset:0x1800
	ds_read_b128 v[92:95], v220 offset:0
	ds_read_b128 v[96:99], v220 offset:0x400
	ds_read_b128 v[120:123], v220 offset:0x800
	ds_read_b128 v[124:127], v220 offset:0xc00
	global_load_lds_dwordx4 v[2:3], off
	v_lshl_add_u64 v[2:3], v[2:3], 0, s[86:87]
	s_mov_b32 m0, s2
	v_add_u32_e32 v221, 0x2000, v0
	global_load_lds_dwordx4 v[2:3], off
	v_mad_u64_u32 v[2:3], s[2:3], s20, v207, v[116:117]
	v_readfirstlane_b32 s2, v221
	v_add_u32_e32 v221, 0x3000, v0
	v_lshl_add_u64 v[2:3], v[2:3], 0, s[28:29]
	s_mov_b32 m0, s2
	s_lshl_b64 s[2:3], s[20:21], 1
	v_readfirstlane_b32 s20, v221
	global_load_lds_dwordx4 v[2:3], off
	v_lshl_add_u64 v[2:3], v[112:113], 0, s[2:3]
	s_mov_b32 m0, s20
	v_add_u32_e32 v0, 0x4000, v0
	global_load_lds_dwordx4 v[2:3], off
	v_lshl_add_u64 v[2:3], v[118:119], 0, s[2:3]
	v_readfirstlane_b32 s2, v0
	s_mov_b32 m0, s2
	s_nop 0
	global_load_lds_dwordx4 v[2:3], off
	s_and_saveexec_b64 s[2:3], s[0:1]
	s_cbranch_execz .LBB0_2313
	s_waitcnt lgkmcnt(8)
	s_nop 0
	s_setprio 1
	v_mfma_f32_16x16x32_bf16 v[100:103], v[60:63], v[24:27], 0
	s_waitcnt lgkmcnt(4)
	v_mfma_f32_16x16x32_bf16 v[60:63], v[60:63], v[20:23], 0
	v_mfma_f32_16x16x32_bf16 v[104:107], v[64:67], v[24:27], 0
	v_mfma_f32_16x16x32_bf16 v[64:67], v[64:67], v[20:23], 0
	v_mfma_f32_16x16x32_bf16 v[180:183], v[68:71], v[24:27], 0
	v_mfma_f32_16x16x32_bf16 v[68:71], v[68:71], v[20:23], 0
	v_mfma_f32_16x16x32_bf16 v[218:221], v[72:75], v[24:27], 0
	v_mfma_f32_16x16x32_bf16 v[72:75], v[72:75], v[20:23], 0
	v_mfma_f32_16x16x32_bf16 v[100:103], v[76:79], v[16:19], v[100:103]
	s_waitcnt lgkmcnt(0)
	v_mfma_f32_16x16x32_bf16 v[60:63], v[76:79], v[12:15], v[60:63]
	v_mfma_f32_16x16x32_bf16 v[76:79], v[80:83], v[16:19], v[104:107]
	v_mfma_f32_16x16x32_bf16 v[64:67], v[80:83], v[12:15], v[64:67]
	v_mfma_f32_16x16x32_bf16 v[80:83], v[84:87], v[16:19], v[180:183]
	v_mfma_f32_16x16x32_bf16 v[68:71], v[84:87], v[12:15], v[68:71]
	v_mfma_f32_16x16x32_bf16 v[84:87], v[88:91], v[16:19], v[218:221]
	v_mfma_f32_16x16x32_bf16 v[72:75], v[88:91], v[12:15], v[72:75]
	v_mfma_f32_16x16x32_bf16 v[182:185], v[92:95], v[8:11], v[100:103]
	v_add_u32_e32 v0, s100, v209
	v_add_u32_e32 v2, s100, v210
	ds_read_b64 v[88:89], v0 offset:0
	v_mfma_f32_16x16x32_bf16 v[218:221], v[96:99], v[8:11], v[76:79]
	ds_read_b64 v[90:91], v2 offset:0
	s_nop 4
	v_fma_f32 v180, v184, s34, -v110
	v_fma_f32 v181, v185, s34, -v110
	v_pk_fma_f32 v[182:183], v[182:183], s[34:35], v[110:111] op_sel_hi:[1,0,0] neg_lo:[0,0,1] neg_hi:[0,0,1]
	v_mfma_f32_16x16x32_bf16 v[222:225], v[120:123], v[8:11], v[80:83]
	v_add_u32_e32 v3, s100, v211
	v_pk_fma_f32 v[128:129], v[220:221], s[34:35], v[110:111] op_sel_hi:[1,0,0] neg_lo:[0,0,1] neg_hi:[0,0,1]
	v_mfma_f32_16x16x32_bf16 v[226:229], v[124:127], v[8:11], v[84:87]
	ds_read_b64 v[84:85], v0 offset:0x800
	ds_read_b64 v[86:87], v2 offset:0x800
	ds_read_b64 v[80:81], v0 offset:0x1000
	v_mfma_f32_16x16x32_bf16 v[104:107], v[92:95], v[4:7], v[60:63]
	ds_read_b64 v[82:83], v2 offset:0x1000
	ds_read_b64 v[76:77], v0 offset:0x1800
	v_max_f32_e32 v0, v180, v181
	v_mfma_f32_16x16x32_bf16 v[92:95], v[124:127], v[4:7], v[72:75]
	v_fma_f32 v126, v218, s34, -v110
	v_fma_f32 v127, v219, s34, -v110
	v_pk_fma_f32 v[124:125], v[222:223], s[34:35], v[110:111] op_sel_hi:[1,0,0] neg_lo:[0,0,1] neg_hi:[0,0,1]
	v_max3_f32 v0, v182, v183, v0
	v_mfma_f32_16x16x32_bf16 v[100:103], v[96:99], v[4:7], v[64:67]
	v_max_f32_e32 v184, v126, v127
	v_max_f32_e32 v185, v128, v129
	v_add_u32_e32 v62, s100, v212
	v_mfma_f32_16x16x32_bf16 v[96:99], v[120:123], v[4:7], v[68:71]
	s_setprio 0
	v_fma_f32 v122, v224, s34, -v110
	v_fma_f32 v123, v225, s34, -v110
	ds_read_b64 v[78:79], v2 offset:0x1800
	ds_read_b64 v[72:73], v3 offset:0
	ds_read_b64 v[74:75], v62 offset:0
	ds_read_b64 v[68:69], v3 offset:0x800
	ds_read_b64 v[70:71], v62 offset:0x800
	ds_read_b64 v[64:65], v3 offset:0x1000
	ds_read_b64 v[66:67], v62 offset:0x1000
	ds_read_b64 v[60:61], v3 offset:0x1800
	v_pk_fma_f32 v[120:121], v[226:227], s[34:35], v[110:111] op_sel_hi:[1,0,0] neg_lo:[0,0,1] neg_hi:[0,0,1]
	v_pk_fma_f32 v[2:3], v[228:229], s[34:35], v[110:111] op_sel_hi:[1,0,0] neg_lo:[0,0,1] neg_hi:[0,0,1]
	v_max3_f32 v0, v0, v184, v185
	v_max_f32_e32 v184, v124, v125
	v_max_f32_e32 v185, v122, v123
	v_max3_f32 v0, v0, v184, v185
	v_max_f32_e32 v184, v120, v121
	v_max_f32_e32 v185, v2, v3
	v_max3_f32 v0, v0, v184, v185
	s_mov_b32 s20, 0x40c00000
	v_cmp_lt_f32_e32 vcc, s20, v0
	ds_read_b64 v[62:63], v62 offset:0x1800
	s_cbranch_vccz .LBB0_2317
	v_mov_b32_e32 v184, v0
	s_nop 1
	v_permlane16_swap_b32_e32 v0, v184
	v_max_f32_e32 v184, v184, v184
	v_max_f32_e32 v0, v0, v0
	v_max_f32_e32 v0, v0, v184
	v_mov_b32_e32 v184, v0
	s_nop 1
	v_permlane32_swap_b32_e32 v0, v184
	v_max3_f32 v0, v0, v184, 0
	v_exp_f32_e64 v184, -v0
	v_pk_add_f32 v[182:183], v[182:183], v[0:1] op_sel_hi:[1,0] neg_lo:[0,1] neg_hi:[0,1]
	v_pk_add_f32 v[180:181], v[180:181], v[0:1] op_sel_hi:[1,0] neg_lo:[0,1] neg_hi:[0,1]
	v_pk_add_f32 v[126:127], v[126:127], v[0:1] op_sel_hi:[1,0] neg_lo:[0,1] neg_hi:[0,1]
	v_pk_add_f32 v[128:129], v[128:129], v[0:1] op_sel_hi:[1,0] neg_lo:[0,1] neg_hi:[0,1]
	v_pk_add_f32 v[124:125], v[124:125], v[0:1] op_sel_hi:[1,0] neg_lo:[0,1] neg_hi:[0,1]
	v_pk_add_f32 v[122:123], v[122:123], v[0:1] op_sel_hi:[1,0] neg_lo:[0,1] neg_hi:[0,1]
	v_pk_add_f32 v[120:121], v[120:121], v[0:1] op_sel_hi:[1,0] neg_lo:[0,1] neg_hi:[0,1]
	v_pk_add_f32 v[2:3], v[2:3], v[0:1] op_sel_hi:[1,0] neg_lo:[0,1] neg_hi:[0,1]
	v_add_f32_e32 v110, v110, v0
	v_mul_f32_e32 v109, v109, v184
	v_pk_mul_f32 v[58:59], v[58:59], v[184:185] op_sel_hi:[1,0]
	v_pk_mul_f32 v[56:57], v[56:57], v[184:185] op_sel_hi:[1,0]
	v_pk_mul_f32 v[50:51], v[50:51], v[184:185] op_sel_hi:[1,0]
	v_pk_mul_f32 v[48:49], v[48:49], v[184:185] op_sel_hi:[1,0]
	v_pk_mul_f32 v[42:43], v[42:43], v[184:185] op_sel_hi:[1,0]
	v_pk_mul_f32 v[40:41], v[40:41], v[184:185] op_sel_hi:[1,0]
	v_pk_mul_f32 v[34:35], v[34:35], v[184:185] op_sel_hi:[1,0]
	v_pk_mul_f32 v[32:33], v[32:33], v[184:185] op_sel_hi:[1,0]
